# L0-down / L1-out epilogues: waves 1-7 touch the first four residual row groups of pass 1 right after publishing the row statistics, so those loads hit L2 after the exchange
# baseline (speedup 1.0000x reference)
.LBB0_877:
	s_or_b64 exec, exec, s[0:1]
	v_readfirstlane_b32 s100, v0
	s_cmp_lt_u32 s100, 64
	s_cbranch_scc1 .Lwarm_skip_l0down
	s_lshl_b32 s100, s30, 5
	s_lshl_b32 s101, s16, 8
	s_or_b32 s100, s101, s100
	v_lshrrev_b32_e32 v254, 2, v0
	v_and_or_b32 v254, v254, 12, s100
	s_lshl_b32 s100, s26, 8
	v_add_u32_e32 v255, s100, v152
	v_lshlrev_b32_e32 v255, 11, v255
	v_lshl_add_u32 v254, v254, 1, v255
	global_load_dwordx2 v[252:253], v254, s[56:57]
	global_load_dwordx2 v[252:253], v254, s[56:57] offset:32
	global_load_dwordx2 v[252:253], v254, s[56:57] offset:256
	global_load_dwordx2 v[252:253], v254, s[56:57] offset:288
	v_add_u32_e32 v255, 0x8000, v254
	global_load_dwordx2 v[252:253], v255, s[56:57]
	global_load_dwordx2 v[252:253], v255, s[56:57] offset:32
	global_load_dwordx2 v[252:253], v255, s[56:57] offset:256
	global_load_dwordx2 v[252:253], v255, s[56:57] offset:288
	v_add_u32_e32 v255, 0x10000, v254
	global_load_dwordx2 v[252:253], v255, s[56:57]
	global_load_dwordx2 v[252:253], v255, s[56:57] offset:32
	global_load_dwordx2 v[252:253], v255, s[56:57] offset:256
	global_load_dwordx2 v[252:253], v255, s[56:57] offset:288
	v_add_u32_e32 v255, 0x18000, v254
	global_load_dwordx2 v[252:253], v255, s[56:57]
	global_load_dwordx2 v[252:253], v255, s[56:57] offset:32
	global_load_dwordx2 v[252:253], v255, s[56:57] offset:256
	global_load_dwordx2 v[252:253], v255, s[56:57] offset:288
.Lwarm_skip_l0down:
	s_cmp_lt_u32 s31, 64
	s_cselect_b64 s[18:19], -1, 0
	s_cmp_gt_u32 s31, 63
	s_cbranch_scc1 .LBB0_894
	s_memrealtime s[0:1]
	s_lshl_b32 s22, s26, 6
	s_ashr_i32 s23, s22, 31
	s_lshl_b64 s[22:23], s[22:23], 2
	s_add_u32 s20, s17, s22
	s_addc_u32 s21, s21, s23
	s_waitcnt lgkmcnt(0)
	v_mov_b32_e32 v133, 0
	v_mov_b64_e32 v[130:131], 0x1e8481
	s_branch .LBB0_881

.LBB0_1472:
	s_or_b64 exec, exec, s[0:1]
	v_readfirstlane_b32 s100, v0
	s_cmp_lt_u32 s100, 64
	s_cbranch_scc1 .Lwarm_skip_l1out
	s_lshl_b32 s100, s40, 5
	s_lshl_b32 s101, s18, 8
	s_or_b32 s100, s101, s100
	v_lshrrev_b32_e32 v254, 2, v0
	v_and_or_b32 v254, v254, 12, s100
	s_lshl_b32 s100, s16, 8
	v_add_u32_e32 v255, s100, v152
	v_lshlrev_b32_e32 v255, 11, v255
	v_lshl_add_u32 v254, v254, 1, v255
	global_load_dwordx2 v[252:253], v254, s[94:95]
	global_load_dwordx2 v[252:253], v254, s[94:95] offset:32
	global_load_dwordx2 v[252:253], v254, s[94:95] offset:256
	global_load_dwordx2 v[252:253], v254, s[94:95] offset:288
	v_add_u32_e32 v255, 0x8000, v254
	global_load_dwordx2 v[252:253], v255, s[94:95]
	global_load_dwordx2 v[252:253], v255, s[94:95] offset:32
	global_load_dwordx2 v[252:253], v255, s[94:95] offset:256
	global_load_dwordx2 v[252:253], v255, s[94:95] offset:288
	v_add_u32_e32 v255, 0x10000, v254
	global_load_dwordx2 v[252:253], v255, s[94:95]
	global_load_dwordx2 v[252:253], v255, s[94:95] offset:32
	global_load_dwordx2 v[252:253], v255, s[94:95] offset:256
	global_load_dwordx2 v[252:253], v255, s[94:95] offset:288
	v_add_u32_e32 v255, 0x18000, v254
	global_load_dwordx2 v[252:253], v255, s[94:95]
	global_load_dwordx2 v[252:253], v255, s[94:95] offset:32
	global_load_dwordx2 v[252:253], v255, s[94:95] offset:256
	global_load_dwordx2 v[252:253], v255, s[94:95] offset:288
.Lwarm_skip_l1out:
	s_cmp_lt_u32 s41, 64
	s_cselect_b64 s[20:21], -1, 0
	s_cmp_gt_u32 s41, 63
	s_cbranch_scc1 .LBB0_1489
	s_memrealtime s[0:1]
	s_lshl_b32 s24, s16, 6
	s_ashr_i32 s25, s24, 31
	s_lshl_b64 s[24:25], s[24:25], 2
	s_add_u32 s22, s19, s24
	s_addc_u32 s23, s23, s25
	s_waitcnt lgkmcnt(0)
	v_mov_b32_e32 v133, 0
	v_mov_b64_e32 v[130:131], 0x1e8481
	s_branch .LBB0_1476
